# GEMM epilogues (in-proj z, out-proj y): output stores marked nt
# speedup vs baseline: 1.0062x; 1.0043x over previous
; #define PG8_STAGE(bufoff, gbase, voff) do { _Pragma("unroll") for (int _i = 0; _i < 2; ++_i) \
;         __builtin_amdgcn_global_load_lds((const unsigned*)((const char*)(gbase) + (voff)[_i]), (LAS unsigned*)(lds + (bufoff) + ldsw + _i * 8192), 16, 0, 0); } while (0)
; #define PG8_LDA(dst, b, h) do { _Pragma("unroll") for (int m = 0; m < 4; ++m) _Pragma("unroll") for (int k = 0; k < 2; ++k) dst[m][k] = *(const LAS bf16x8*)(lds + PG8_SA(b, h) + aoff + m * 2048 + k * 1024); } while (0)
; #define PG8_LDB(dst, b, h) do { _Pragma("unroll") for (int n = 0; n < 2; ++n) _Pragma("unroll") for (int k = 0; k < 2; ++k) dst[n][k] = *(const LAS bf16x8*)(lds + PG8_SB(b, h) + boff + n * 2048 + k * 1024); } while (0)
; #define PG8_MMA(ai, bj, At, Bt) do { __builtin_amdgcn_s_setprio(1); _Pragma("unroll") for (int m = 0; m < 4; ++m) _Pragma("unroll") for (int n = 0; n < 2; ++n) _Pragma("unroll") for (int k = 0; k < 2; ++k) \
;         acc[ai][bj][m][n] = __builtin_amdgcn_mfma_f32_16x16x32_bf16(Bt[n][k], At[m][k], acc[ai][bj][m][n], 0, 0, 0); __builtin_amdgcn_s_setprio(0); } while (0)
; #define PG8_WAIT_V(n) asm volatile("s_waitcnt vmcnt(" #n ")" ::: "memory")
; #define PG8_WAIT_L(n) asm volatile("s_waitcnt lgkmcnt(" #n ")" ::: "memory")
; #define PG8_BAR __builtin_amdgcn_s_barrier()
; #define PG8_SCHED __builtin_amdgcn_sched_barrier(0)
; template <class Epi>
; DI void gemm_phase(LAS unsigned char* lds, const Gemm g, const StaticOrder& S, const Epi& E, const int tid) {
;     ...
;             PG8_LDB(B0, 0, 0); PG8_SCHED; PG8_LDA(At, 0, 0); PG8_STAGE(PG8_SA(1, 1), a1 + hstepA, voffA);
;             PG8_WAIT_L(8); PG8_BAR; PG8_WAIT_L(0); PG8_MMA(0, 0, At, B0); PG8_BAR; PG8_SCHED;
;             PG8_LDB(B1, 0, 1); PG8_STAGE(PG8_SB(0, 0), b2, voffB);
;             PG8_BAR; PG8_WAIT_L(0); PG8_MMA(0, 1, At, B1); PG8_BAR;
;             PG8_LDA(At, 0, 1); PG8_STAGE(PG8_SA(0, 0), a2, voffA);
;             PG8_BAR; PG8_WAIT_L(0); PG8_MMA(1, 0, At, B0); PG8_BAR; PG8_SCHED;
;             PG8_STAGE(PG8_SB(0, 1), b2 + hstepB, voffB);
;             PG8_WAIT_V(6); PG8_BAR; PG8_MMA(1, 1, At, B1); PG8_BAR;
.LBB0_62:
	s_add_i32 s69, 0, 0x10000
	ds_read_b128 v[158:161], v241
	ds_read_b128 v[162:165], v241 offset:1024
	ds_read_b128 v[166:169], v241 offset:2048
	ds_read_b128 v[178:181], v241 offset:3072
	s_add_i32 m0, s41, 0xc000
	ds_read_b128 v[182:185], v151
	ds_read_b128 v[186:189], v151 offset:1024
	ds_read_b128 v[190:193], v151 offset:2048
	ds_read_b128 v[194:197], v151 offset:3072
	ds_read_b128 v[198:201], v151 offset:4096
	ds_read_b128 v[202:205], v151 offset:5120
	ds_read_b128 v[206:209], v151 offset:6144
	ds_read_b128 v[210:213], v151 offset:7168
	global_load_lds_dwordx4 v138, s[86:87]
	s_add_i32 m0, s41, 0xe000
	s_nop 0
	global_load_lds_dwordx4 v140, s[86:87]
	s_waitcnt lgkmcnt(8)
	s_barrier
	s_waitcnt lgkmcnt(0)
	s_setprio 1
	s_waitcnt lgkmcnt(0)
	v_mfma_f32_16x16x32_bf16 v[126:129], v[158:161], v[182:185], v[126:129]
	v_mfma_f32_16x16x32_bf16 v[122:125], v[166:169], v[182:185], v[122:125]
	v_mfma_f32_16x16x32_bf16 v[118:121], v[158:161], v[190:193], v[118:121]
	v_mfma_f32_16x16x32_bf16 v[114:117], v[166:169], v[190:193], v[114:117]
	v_mfma_f32_16x16x32_bf16 v[102:105], v[158:161], v[198:201], v[102:105]
	v_mfma_f32_16x16x32_bf16 v[98:101], v[166:169], v[198:201], v[98:101]
	v_mfma_f32_16x16x32_bf16 v[86:89], v[158:161], v[206:209], v[86:89]
	v_mfma_f32_16x16x32_bf16 v[82:85], v[166:169], v[206:209], v[82:85]
	v_mfma_f32_16x16x32_bf16 v[126:129], v[162:165], v[186:189], v[126:129]
	v_mfma_f32_16x16x32_bf16 v[122:125], v[178:181], v[186:189], v[122:125]
	v_mfma_f32_16x16x32_bf16 v[118:121], v[162:165], v[194:197], v[118:121]
	v_mfma_f32_16x16x32_bf16 v[114:117], v[178:181], v[194:197], v[114:117]
	v_mfma_f32_16x16x32_bf16 v[102:105], v[162:165], v[202:205], v[102:105]
	v_mfma_f32_16x16x32_bf16 v[98:101], v[178:181], v[202:205], v[98:101]
	v_mfma_f32_16x16x32_bf16 v[86:89], v[162:165], v[210:213], v[86:89]
	v_mfma_f32_16x16x32_bf16 v[82:85], v[178:181], v[210:213], v[82:85]
	s_setprio 0
	s_barrier
	s_add_i32 s78, 0, 0x14000
	s_add_i32 s69, s69, s26
	ds_read_b128 v[214:217], v242
	ds_read_b128 v[218:221], v242 offset:1024
	ds_read_b128 v[222:225], v242 offset:2048
	ds_read_b128 v[226:229], v242 offset:3072
	s_mov_b32 m0, s69
	s_nop 0
	global_load_lds_dwordx4 v0, s[6:7]
	s_add_i32 m0, s69, 0x2000
	s_nop 0
	global_load_lds_dwordx4 v130, s[6:7]
	s_barrier
	s_waitcnt lgkmcnt(0)
	s_setprio 1
	s_waitcnt lgkmcnt(0)
	v_mfma_f32_16x16x32_bf16 v[110:113], v[214:217], v[182:185], v[110:113]
	v_mfma_f32_16x16x32_bf16 v[106:109], v[222:225], v[182:185], v[106:109]
	v_mfma_f32_16x16x32_bf16 v[94:97], v[214:217], v[190:193], v[94:97]
	v_mfma_f32_16x16x32_bf16 v[90:93], v[222:225], v[190:193], v[90:93]
	v_mfma_f32_16x16x32_bf16 v[78:81], v[214:217], v[198:201], v[78:81]
	v_mfma_f32_16x16x32_bf16 v[74:77], v[222:225], v[198:201], v[74:77]
	v_mfma_f32_16x16x32_bf16 v[70:73], v[214:217], v[206:209], v[70:73]
	v_mfma_f32_16x16x32_bf16 v[66:69], v[222:225], v[206:209], v[66:69]
	v_mfma_f32_16x16x32_bf16 v[110:113], v[218:221], v[186:189], v[110:113]
	v_mfma_f32_16x16x32_bf16 v[106:109], v[226:229], v[186:189], v[106:109]
	v_mfma_f32_16x16x32_bf16 v[94:97], v[218:221], v[194:197], v[94:97]
	v_mfma_f32_16x16x32_bf16 v[90:93], v[226:229], v[194:197], v[90:93]
	v_mfma_f32_16x16x32_bf16 v[78:81], v[218:221], v[202:205], v[78:81]
	v_mfma_f32_16x16x32_bf16 v[74:77], v[226:229], v[202:205], v[74:77]
	v_mfma_f32_16x16x32_bf16 v[70:73], v[218:221], v[210:213], v[70:73]
	v_mfma_f32_16x16x32_bf16 v[66:69], v[226:229], v[210:213], v[66:69]
	s_setprio 0
	s_mov_b32 m0, s41
	s_barrier
	ds_read_b128 v[182:185], v151 offset:16384
	ds_read_b128 v[186:189], v151 offset:17408
	ds_read_b128 v[190:193], v151 offset:18432
	ds_read_b128 v[194:197], v151 offset:19456
	ds_read_b128 v[198:201], v151 offset:20480
	ds_read_b128 v[202:205], v151 offset:21504
	ds_read_b128 v[206:209], v151 offset:22528
	ds_read_b128 v[210:213], v151 offset:23552
	global_load_lds_dwordx4 v134, s[50:51]
	s_mov_b32 m0, s55
	s_nop 0
	global_load_lds_dwordx4 v132, s[50:51]
	s_barrier
	s_waitcnt lgkmcnt(0)
	s_setprio 1
	s_waitcnt lgkmcnt(0)
	v_mfma_f32_16x16x32_bf16 v[62:65], v[158:161], v[182:185], v[62:65]
	v_mfma_f32_16x16x32_bf16 v[58:61], v[166:169], v[182:185], v[58:61]
	v_mfma_f32_16x16x32_bf16 v[54:57], v[158:161], v[190:193], v[54:57]
	v_mfma_f32_16x16x32_bf16 v[50:53], v[166:169], v[190:193], v[50:53]
	v_mfma_f32_16x16x32_bf16 v[38:41], v[158:161], v[198:201], v[38:41]
	v_mfma_f32_16x16x32_bf16 v[34:37], v[166:169], v[198:201], v[34:37]
	v_mfma_f32_16x16x32_bf16 v[22:25], v[158:161], v[206:209], v[22:25]
	v_mfma_f32_16x16x32_bf16 v[18:21], v[166:169], v[206:209], v[18:21]
	v_mfma_f32_16x16x32_bf16 v[62:65], v[162:165], v[186:189], v[62:65]
	v_mfma_f32_16x16x32_bf16 v[58:61], v[178:181], v[186:189], v[58:61]
	v_mfma_f32_16x16x32_bf16 v[54:57], v[162:165], v[194:197], v[54:57]
	v_mfma_f32_16x16x32_bf16 v[50:53], v[178:181], v[194:197], v[50:53]
	v_mfma_f32_16x16x32_bf16 v[38:41], v[162:165], v[202:205], v[38:41]
	v_mfma_f32_16x16x32_bf16 v[34:37], v[178:181], v[202:205], v[34:37]
	v_mfma_f32_16x16x32_bf16 v[22:25], v[162:165], v[210:213], v[22:25]
	v_mfma_f32_16x16x32_bf16 v[18:21], v[178:181], v[210:213], v[18:21]
	s_setprio 0
	s_barrier
	s_add_u32 s86, s6, 0x80000
	s_addc_u32 s87, s7, 0
	s_add_i32 s69, s78, s26
	s_mov_b32 m0, s69
	s_nop 0
	global_load_lds_dwordx4 v0, s[86:87]
	s_add_i32 m0, s69, 0x2000
	s_nop 0
	global_load_lds_dwordx4 v130, s[86:87]
	s_waitcnt vmcnt(6)
	s_barrier
; #define PG8_STAGE(bufoff, gbase, voff) do { _Pragma("unroll") for (int _i = 0; _i < 2; ++_i) \
;         __builtin_amdgcn_global_load_lds((const unsigned*)((const char*)(gbase) + (voff)[_i]), (LAS unsigned*)(lds + (bufoff) + ldsw + _i * 8192), 16, 0, 0); } while (0)
; #define PG8_LDA(dst, b, h) do { _Pragma("unroll") for (int m = 0; m < 4; ++m) _Pragma("unroll") for (int k = 0; k < 2; ++k) dst[m][k] = *(const LAS bf16x8*)(lds + PG8_SA(b, h) + aoff + m * 2048 + k * 1024); } while (0)
; #define PG8_LDB(dst, b, h) do { _Pragma("unroll") for (int n = 0; n < 2; ++n) _Pragma("unroll") for (int k = 0; k < 2; ++k) dst[n][k] = *(const LAS bf16x8*)(lds + PG8_SB(b, h) + boff + n * 2048 + k * 1024); } while (0)
; #define PG8_MMA(ai, bj, At, Bt) do { __builtin_amdgcn_s_setprio(1); _Pragma("unroll") for (int m = 0; m < 4; ++m) _Pragma("unroll") for (int n = 0; n < 2; ++n) _Pragma("unroll") for (int k = 0; k < 2; ++k) \
;         acc[ai][bj][m][n] = __builtin_amdgcn_mfma_f32_16x16x32_bf16(Bt[n][k], At[m][k], acc[ai][bj][m][n], 0, 0, 0); __builtin_amdgcn_s_setprio(0); } while (0)
; #define PG8_WAIT_V(n) asm volatile("s_waitcnt vmcnt(" #n ")" ::: "memory")
; #define PG8_WAIT_L(n) asm volatile("s_waitcnt lgkmcnt(" #n ")" ::: "memory")
; #define PG8_BAR __builtin_amdgcn_s_barrier()
; #define PG8_SCHED __builtin_amdgcn_sched_barrier(0)
; template <class Epi>
; DI void gemm_phase(LAS unsigned char* lds, const Gemm g, const StaticOrder& S, const Epi& E, const int tid) {
;     ...
;             PG8_WAIT_V(6); PG8_BAR; PG8_MMA(1, 1, At, B1); PG8_BAR;
;             PG8_LDB(B0, 1, 0); PG8_SCHED; PG8_LDA(At, 1, 0); PG8_STAGE(PG8_SA(0, 1), a2 + hstepA, voffA);
;             PG8_WAIT_L(8); PG8_BAR; PG8_WAIT_L(0); PG8_MMA(0, 0, At, B0); PG8_BAR; PG8_SCHED;
;             PG8_LDB(B1, 1, 1); PG8_STAGE(PG8_SB(1, 0), b3, voffB);
;             PG8_BAR; PG8_WAIT_L(0); PG8_MMA(0, 1, At, B1); PG8_BAR;
;             PG8_LDA(At, 1, 1); PG8_STAGE(PG8_SA(1, 0), a3, voffA);
;             PG8_BAR; PG8_WAIT_L(0); PG8_MMA(1, 0, At, B0); PG8_BAR; PG8_SCHED;
	s_setprio 1
	v_mfma_f32_16x16x32_bf16 v[46:49], v[214:217], v[182:185], v[46:49]
	v_mfma_f32_16x16x32_bf16 v[42:45], v[222:225], v[182:185], v[42:45]
	v_mfma_f32_16x16x32_bf16 v[30:33], v[214:217], v[190:193], v[30:33]
	v_mfma_f32_16x16x32_bf16 v[26:29], v[222:225], v[190:193], v[26:29]
	v_mfma_f32_16x16x32_bf16 v[14:17], v[214:217], v[198:201], v[14:17]
	v_mfma_f32_16x16x32_bf16 v[10:13], v[222:225], v[198:201], v[10:13]
	v_mfma_f32_16x16x32_bf16 v[6:9], v[214:217], v[206:209], v[6:9]
	v_mfma_f32_16x16x32_bf16 v[2:5], v[222:225], v[206:209], v[2:5]
	v_mfma_f32_16x16x32_bf16 v[46:49], v[218:221], v[186:189], v[46:49]
	v_mfma_f32_16x16x32_bf16 v[42:45], v[226:229], v[186:189], v[42:45]
	v_mfma_f32_16x16x32_bf16 v[30:33], v[218:221], v[194:197], v[30:33]
	v_mfma_f32_16x16x32_bf16 v[26:29], v[226:229], v[194:197], v[26:29]
	v_mfma_f32_16x16x32_bf16 v[14:17], v[218:221], v[202:205], v[14:17]
	v_mfma_f32_16x16x32_bf16 v[10:13], v[226:229], v[202:205], v[10:13]
	v_mfma_f32_16x16x32_bf16 v[6:9], v[218:221], v[210:213], v[6:9]
	v_mfma_f32_16x16x32_bf16 v[2:5], v[226:229], v[210:213], v[2:5]
	s_setprio 0
	s_add_i32 s69, 0, 0x18000
	s_barrier
	ds_read_b128 v[158:161], v243
	ds_read_b128 v[162:165], v243 offset:1024
	ds_read_b128 v[166:169], v243 offset:2048
	ds_read_b128 v[178:181], v243 offset:3072
	s_add_u32 s50, s50, 0x80000
	s_addc_u32 s51, s51, 0
	s_mov_b32 m0, s56
	s_nop 0
	ds_read_b128 v[182:185], v151 offset:32768
	ds_read_b128 v[186:189], v151 offset:33792
	ds_read_b128 v[190:193], v151 offset:34816
	ds_read_b128 v[194:197], v151 offset:35840
	ds_read_b128 v[198:201], v151 offset:36864
	ds_read_b128 v[202:205], v151 offset:37888
	ds_read_b128 v[206:209], v151 offset:38912
	ds_read_b128 v[210:213], v151 offset:39936
	global_load_lds_dwordx4 v134, s[50:51]
	s_mov_b32 m0, s57
	s_nop 0
	global_load_lds_dwordx4 v132, s[50:51]
	s_waitcnt lgkmcnt(8)
	s_barrier
	s_waitcnt lgkmcnt(0)
	s_setprio 1
	s_waitcnt lgkmcnt(0)
	v_mfma_f32_16x16x32_bf16 v[126:129], v[158:161], v[182:185], v[126:129]
	v_mfma_f32_16x16x32_bf16 v[122:125], v[166:169], v[182:185], v[122:125]
	v_mfma_f32_16x16x32_bf16 v[118:121], v[158:161], v[190:193], v[118:121]
	v_mfma_f32_16x16x32_bf16 v[114:117], v[166:169], v[190:193], v[114:117]
	v_mfma_f32_16x16x32_bf16 v[102:105], v[158:161], v[198:201], v[102:105]
	v_mfma_f32_16x16x32_bf16 v[98:101], v[166:169], v[198:201], v[98:101]
	v_mfma_f32_16x16x32_bf16 v[86:89], v[158:161], v[206:209], v[86:89]
	v_mfma_f32_16x16x32_bf16 v[82:85], v[166:169], v[206:209], v[82:85]
	v_mfma_f32_16x16x32_bf16 v[126:129], v[162:165], v[186:189], v[126:129]
	v_mfma_f32_16x16x32_bf16 v[122:125], v[178:181], v[186:189], v[122:125]
	v_mfma_f32_16x16x32_bf16 v[118:121], v[162:165], v[194:197], v[118:121]
	v_mfma_f32_16x16x32_bf16 v[114:117], v[178:181], v[194:197], v[114:117]
	v_mfma_f32_16x16x32_bf16 v[102:105], v[162:165], v[202:205], v[102:105]
	v_mfma_f32_16x16x32_bf16 v[98:101], v[178:181], v[202:205], v[98:101]
	v_mfma_f32_16x16x32_bf16 v[86:89], v[162:165], v[210:213], v[86:89]
	v_mfma_f32_16x16x32_bf16 v[82:85], v[178:181], v[210:213], v[82:85]
	s_setprio 0
	s_barrier
	s_add_i32 s50, 0, 0x1c000
	s_add_i32 s51, s69, s26
	s_add_u32 s86, s6, s84
	s_addc_u32 s87, s7, s85
	s_mov_b32 m0, s51
	ds_read_b128 v[214:217], v244
	ds_read_b128 v[218:221], v244 offset:1024
	ds_read_b128 v[222:225], v244 offset:2048
	ds_read_b128 v[226:229], v244 offset:3072
	global_load_lds_dwordx4 v0, s[86:87]
	s_add_i32 m0, s51, 0x2000
	s_nop 0
	global_load_lds_dwordx4 v130, s[86:87]
	s_barrier
	s_waitcnt lgkmcnt(0)
	s_setprio 1
	s_waitcnt lgkmcnt(0)
	v_mfma_f32_16x16x32_bf16 v[110:113], v[214:217], v[182:185], v[110:113]
	v_mfma_f32_16x16x32_bf16 v[106:109], v[222:225], v[182:185], v[106:109]
	v_mfma_f32_16x16x32_bf16 v[94:97], v[214:217], v[190:193], v[94:97]
	v_mfma_f32_16x16x32_bf16 v[90:93], v[222:225], v[190:193], v[90:93]
	v_mfma_f32_16x16x32_bf16 v[78:81], v[214:217], v[198:201], v[78:81]
	v_mfma_f32_16x16x32_bf16 v[74:77], v[222:225], v[198:201], v[74:77]
	v_mfma_f32_16x16x32_bf16 v[70:73], v[214:217], v[206:209], v[70:73]
	v_mfma_f32_16x16x32_bf16 v[66:69], v[222:225], v[206:209], v[66:69]
	v_mfma_f32_16x16x32_bf16 v[110:113], v[218:221], v[186:189], v[110:113]
	v_mfma_f32_16x16x32_bf16 v[106:109], v[226:229], v[186:189], v[106:109]
	v_mfma_f32_16x16x32_bf16 v[94:97], v[218:221], v[194:197], v[94:97]
	v_mfma_f32_16x16x32_bf16 v[90:93], v[226:229], v[194:197], v[90:93]
	v_mfma_f32_16x16x32_bf16 v[78:81], v[218:221], v[202:205], v[78:81]
	v_mfma_f32_16x16x32_bf16 v[74:77], v[226:229], v[202:205], v[74:77]
	v_mfma_f32_16x16x32_bf16 v[70:73], v[218:221], v[210:213], v[70:73]
	v_mfma_f32_16x16x32_bf16 v[66:69], v[226:229], v[210:213], v[66:69]
	s_setprio 0
	s_mov_b32 m0, s59
	s_nop 0
	s_barrier
	ds_read_b128 v[182:185], v151 offset:49152
	ds_read_b128 v[186:189], v151 offset:50176
	ds_read_b128 v[190:193], v151 offset:51200
	ds_read_b128 v[194:197], v151 offset:52224
	ds_read_b128 v[198:201], v151 offset:53248
	ds_read_b128 v[202:205], v151 offset:54272
	ds_read_b128 v[206:209], v151 offset:55296
	ds_read_b128 v[210:213], v151 offset:56320
	global_load_lds_dwordx4 v134, s[8:9]
	s_mov_b32 m0, s60
	s_nop 0
	global_load_lds_dwordx4 v132, s[8:9]
	s_barrier
; #define PG8_STAGE(bufoff, gbase, voff) do { _Pragma("unroll") for (int _i = 0; _i < 2; ++_i) \
;         __builtin_amdgcn_global_load_lds((const unsigned*)((const char*)(gbase) + (voff)[_i]), (LAS unsigned*)(lds + (bufoff) + ldsw + _i * 8192), 16, 0, 0); } while (0)
; #define PG8_MMA(ai, bj, At, Bt) do { __builtin_amdgcn_s_setprio(1); _Pragma("unroll") for (int m = 0; m < 4; ++m) _Pragma("unroll") for (int n = 0; n < 2; ++n) _Pragma("unroll") for (int k = 0; k < 2; ++k) \
;         acc[ai][bj][m][n] = __builtin_amdgcn_mfma_f32_16x16x32_bf16(Bt[n][k], At[m][k], acc[ai][bj][m][n], 0, 0, 0); __builtin_amdgcn_s_setprio(0); } while (0)
; #define PG8_WAIT_V(n) asm volatile("s_waitcnt vmcnt(" #n ")" ::: "memory")
; #define PG8_WAIT_L(n) asm volatile("s_waitcnt lgkmcnt(" #n ")" ::: "memory")
; #define PG8_BAR __builtin_amdgcn_s_barrier()
; #define PG8_SCHED __builtin_amdgcn_sched_barrier(0)
; template <class Epi>
; DI void gemm_phase(LAS unsigned char* lds, const Gemm g, const StaticOrder& S, const Epi& E, const int tid) {
;     ...
;         for (int t = 0; t < nt; t += 2) {
;             const bool last = (t == nt - 2);
;             const char* a1 = cA + PG8_KTA(t + 1);
;             const char* a2 = last ? nA : cA + PG8_KTA(t + 2); const char* b2 = last ? nB : cB + (size_t)(t + 2) * kstep;
;             const char* a3 = last ? nA + PG8_KTA(1) : cA + PG8_KTA(t + 3); const char* b3 = b2 + kstep;
;     ...
;             PG8_BAR; PG8_WAIT_L(0); PG8_MMA(1, 0, At, B0); PG8_BAR; PG8_SCHED;
;             PG8_STAGE(PG8_SB(1, 1), b3 + hstepB, voffB);
;             PG8_WAIT_V(6); PG8_BAR; PG8_MMA(1, 1, At, B1); PG8_BAR;
	s_waitcnt lgkmcnt(0)
	s_setprio 1
	s_waitcnt lgkmcnt(0)
	v_mfma_f32_16x16x32_bf16 v[62:65], v[158:161], v[182:185], v[62:65]
	v_mfma_f32_16x16x32_bf16 v[58:61], v[166:169], v[182:185], v[58:61]
	v_mfma_f32_16x16x32_bf16 v[54:57], v[158:161], v[190:193], v[54:57]
	v_mfma_f32_16x16x32_bf16 v[50:53], v[166:169], v[190:193], v[50:53]
	v_mfma_f32_16x16x32_bf16 v[38:41], v[158:161], v[198:201], v[38:41]
	v_mfma_f32_16x16x32_bf16 v[34:37], v[166:169], v[198:201], v[34:37]
	v_mfma_f32_16x16x32_bf16 v[22:25], v[158:161], v[206:209], v[22:25]
	v_mfma_f32_16x16x32_bf16 v[18:21], v[166:169], v[206:209], v[18:21]
	v_mfma_f32_16x16x32_bf16 v[62:65], v[162:165], v[186:189], v[62:65]
	v_mfma_f32_16x16x32_bf16 v[58:61], v[178:181], v[186:189], v[58:61]
	v_mfma_f32_16x16x32_bf16 v[54:57], v[162:165], v[194:197], v[54:57]
	v_mfma_f32_16x16x32_bf16 v[50:53], v[178:181], v[194:197], v[50:53]
	v_mfma_f32_16x16x32_bf16 v[38:41], v[162:165], v[202:205], v[38:41]
	v_mfma_f32_16x16x32_bf16 v[34:37], v[178:181], v[202:205], v[34:37]
	v_mfma_f32_16x16x32_bf16 v[22:25], v[162:165], v[210:213], v[22:25]
	v_mfma_f32_16x16x32_bf16 v[18:21], v[178:181], v[210:213], v[18:21]
	s_setprio 0
	s_barrier
	s_add_u32 s6, s6, 0x80080
	s_addc_u32 s7, s7, 0
	s_add_i32 s8, s50, s26
	s_mov_b32 m0, s8
	s_nop 0
	global_load_lds_dwordx4 v0, s[6:7]
	s_add_i32 m0, s8, 0x2000
	s_nop 0
	global_load_lds_dwordx4 v130, s[6:7]
	s_waitcnt vmcnt(6)
	s_barrier
	s_setprio 1
	v_mfma_f32_16x16x32_bf16 v[46:49], v[214:217], v[182:185], v[46:49]
	v_mfma_f32_16x16x32_bf16 v[42:45], v[222:225], v[182:185], v[42:45]
	v_mfma_f32_16x16x32_bf16 v[30:33], v[214:217], v[190:193], v[30:33]
	v_mfma_f32_16x16x32_bf16 v[26:29], v[222:225], v[190:193], v[26:29]
	v_mfma_f32_16x16x32_bf16 v[14:17], v[214:217], v[198:201], v[14:17]
	v_mfma_f32_16x16x32_bf16 v[10:13], v[222:225], v[198:201], v[10:13]
	v_mfma_f32_16x16x32_bf16 v[6:9], v[214:217], v[206:209], v[6:9]
	v_mfma_f32_16x16x32_bf16 v[2:5], v[222:225], v[206:209], v[2:5]
	v_mfma_f32_16x16x32_bf16 v[46:49], v[218:221], v[186:189], v[46:49]
	v_mfma_f32_16x16x32_bf16 v[42:45], v[226:229], v[186:189], v[42:45]
	v_mfma_f32_16x16x32_bf16 v[30:33], v[218:221], v[194:197], v[30:33]
	v_mfma_f32_16x16x32_bf16 v[26:29], v[226:229], v[194:197], v[26:29]
	v_mfma_f32_16x16x32_bf16 v[14:17], v[218:221], v[202:205], v[14:17]
	v_mfma_f32_16x16x32_bf16 v[10:13], v[226:229], v[202:205], v[10:13]
	v_mfma_f32_16x16x32_bf16 v[6:9], v[218:221], v[210:213], v[6:9]
	v_mfma_f32_16x16x32_bf16 v[2:5], v[226:229], v[210:213], v[2:5]
	s_setprio 0
	s_add_i32 s68, s68, 2
	s_add_u32 s4, s4, 0x100
	s_addc_u32 s5, s5, 0
	s_add_u32 s6, s44, s4
	s_addc_u32 s7, s45, s5
	s_add_u32 s8, s6, 0x100
	s_addc_u32 s9, s7, 0
	s_add_u32 s69, s66, s4
	s_addc_u32 s78, s67, s5
	s_add_u32 s86, s6, 0x180
	s_addc_u32 s87, s7, 0
	s_cmpk_eq_i32 s4, 0xf00
	s_cselect_b32 s51, s30, s9
	s_cselect_b32 s50, s31, s8
	s_cselect_b32 s7, s39, s78
	s_cselect_b32 s6, s43, s69
	s_cselect_b32 s9, s65, s87
	s_cselect_b32 s8, s64, s86
	s_add_u32 s86, s44, s4
	s_addc_u32 s87, s45, s5
	s_add_u32 s86, s86, 0x80080
	s_addc_u32 s87, s87, 0
	s_cmp_gt_u32 s68, 29
	s_barrier
	s_cbranch_scc0 .LBB0_62
; DI unsigned pk2(float a, float b) { f32x2 v = {a, b}; bf16v2 r = __builtin_convertvector(v, bf16v2); return __builtin_bit_cast(unsigned, r); }
; #define PG8_WAIT_V(n) asm volatile("s_waitcnt vmcnt(" #n ")" ::: "memory")
; #define PG8_BAR __builtin_amdgcn_s_barrier()
;     DI void operator()(const f32x4 (&acc)[2][2][4][2], const Unit& u, int wr, int wc, int fr, int fq) const {
;         if (nt) {
;             unsigned char* tb = (unsigned char*)O + ((size_t)(u.pm * nt + u.pn) << 17) + (wr * 4 + wc) * 1024 + (fq * 16 + fr) * 16;
; #pragma unroll
;             for (int ai = 0; ai < 2; ++ai)
; #pragma unroll
;                 for (int m = 0; m < 4; ++m)
; #pragma unroll
;                     for (int bj = 0; bj < 2; ++bj) { const f32x4 v0 = acc[ai][bj][m][0], v1 = acc[ai][bj][m][1];
;                         u32x4 w; w.x = pk2(v0[0], v0[1]); w.y = pk2(v0[2], v0[3]); w.z = pk2(v1[0], v1[1]); w.w = pk2(v1[2], v1[3]);
;                         *(u32x4*)(tb + ((ai * 4 + m) * 2 + bj) * 8192) = w; }
;             return;
; template <class Epi>
; DI void gemm_phase(LAS unsigned char* lds, const Gemm g, const StaticOrder& S, const Epi& E, const int tid) {
;     ...
;         if (!has_next) break;
; #pragma unroll
;         for (int a = 0; a < 2; ++a)
; #pragma unroll
;             for (int b = 0; b < 2; ++b)
; #pragma unroll
;                 for (int m = 0; m < 4; ++m)
; #pragma unroll
;                     for (int n = 0; n < 2; ++n) acc[a][b][m][n] = (f32x4){0.f, 0.f, 0.f, 0.f};
;         cur = nxt; cA = nA; cB = nB; ++ui;
;     }
;     PG8_WAIT_V(0);
;     if (wr == 0) PG8_BAR;
	s_mul_i32 s4, s40, s58
	s_add_i32 s4, s4, s63
	s_ashr_i32 s5, s4, 31
	s_lshl_b64 s[4:5], s[4:5], 17
	v_lshl_add_u64 v[144:145], v[136:137], 0, s[4:5]
	s_movk_i32 s4, 0x2000
	v_cvt_pk_bf16_f32 v110, v110, v111
	v_cvt_pk_bf16_f32 v111, v112, v113
	v_cvt_pk_bf16_f32 v112, v106, v107
	v_add_co_u32_e32 v106, vcc, s4, v144
	v_cvt_pk_bf16_f32 v113, v108, v109
	s_nop 0
	v_addc_co_u32_e32 v107, vcc, 0, v145, vcc
	global_store_dwordx4 v[106:107], v[110:113], off nt
	s_movk_i32 s4, 0x6000
	v_cvt_pk_bf16_f32 v94, v94, v95
	v_add_co_u32_e32 v110, vcc, s3, v144
	v_cvt_pk_bf16_f32 v95, v96, v97
	s_nop 0
	v_addc_co_u32_e32 v111, vcc, 0, v145, vcc
	v_cvt_pk_bf16_f32 v96, v90, v91
	v_add_co_u32_e32 v90, vcc, s4, v144
	v_cvt_pk_bf16_f32 v97, v92, v93
	s_nop 0
	v_addc_co_u32_e32 v91, vcc, 0, v145, vcc
	s_mov_b32 s4, 0x8000
	global_store_dwordx4 v[90:91], v[94:97], off nt
	v_cvt_pk_bf16_f32 v78, v78, v79
	v_cvt_pk_bf16_f32 v79, v80, v81
	v_add_co_u32_e32 v94, vcc, s4, v144
	s_mov_b32 s4, 0xa000
	s_nop 0
	v_addc_co_u32_e32 v95, vcc, 0, v145, vcc
	v_cvt_pk_bf16_f32 v80, v74, v75
	v_add_co_u32_e32 v74, vcc, s4, v144
	v_cvt_pk_bf16_f32 v81, v76, v77
	s_nop 0
	v_addc_co_u32_e32 v75, vcc, 0, v145, vcc
	global_store_dwordx4 v[74:75], v[78:81], off nt
	s_mov_b32 s4, 0xe000
	v_cvt_pk_bf16_f32 v70, v70, v71
	v_add_co_u32_e32 v78, vcc, s13, v144
	v_cvt_pk_bf16_f32 v71, v72, v73
	s_nop 0
	v_addc_co_u32_e32 v79, vcc, 0, v145, vcc
	v_cvt_pk_bf16_f32 v72, v66, v67
	v_add_co_u32_e32 v66, vcc, s4, v144
	s_mov_b32 s4, 0x10000
	s_nop 0
	v_addc_co_u32_e32 v67, vcc, 0, v145, vcc
	v_cvt_pk_bf16_f32 v62, v62, v63
	v_cvt_pk_bf16_f32 v63, v64, v65
	v_cvt_pk_bf16_f32 v64, v58, v59
	v_add_co_u32_e32 v58, vcc, s4, v144
	s_mov_b32 s4, 0x12000
	s_nop 0
	v_addc_co_u32_e32 v59, vcc, 0, v145, vcc
	v_cvt_pk_bf16_f32 v46, v46, v47
	v_cvt_pk_bf16_f32 v47, v48, v49
	v_cvt_pk_bf16_f32 v48, v42, v43
	v_add_co_u32_e32 v42, vcc, s4, v144
	v_cvt_pk_bf16_f32 v49, v44, v45
	s_nop 0
	v_addc_co_u32_e32 v43, vcc, 0, v145, vcc
	s_mov_b32 s4, 0x14000
	global_store_dwordx4 v[42:43], v[46:49], off nt
	v_cvt_pk_bf16_f32 v30, v30, v31
	v_cvt_pk_bf16_f32 v31, v32, v33
	v_add_co_u32_e32 v46, vcc, s4, v144
	s_mov_b32 s4, 0x16000
	s_nop 0
	v_addc_co_u32_e32 v47, vcc, 0, v145, vcc
	v_cvt_pk_bf16_f32 v32, v26, v27
	v_add_co_u32_e32 v26, vcc, s4, v144
	v_cvt_pk_bf16_f32 v33, v28, v29
	s_nop 0
	v_addc_co_u32_e32 v27, vcc, 0, v145, vcc
	s_mov_b32 s4, 0x18000
	global_store_dwordx4 v[26:27], v[30:33], off nt
	v_cvt_pk_bf16_f32 v14, v14, v15
	v_cvt_pk_bf16_f32 v15, v16, v17
	v_add_co_u32_e32 v30, vcc, s4, v144
	s_mov_b32 s4, 0x1a000
	s_nop 0
	v_addc_co_u32_e32 v31, vcc, 0, v145, vcc
	v_cvt_pk_bf16_f32 v16, v10, v11
	v_add_co_u32_e32 v10, vcc, s4, v144
	v_cvt_pk_bf16_f32 v17, v12, v13
	s_nop 0
	v_addc_co_u32_e32 v11, vcc, 0, v145, vcc
	s_mov_b32 s4, 0x1c000
	global_store_dwordx4 v[10:11], v[14:17], off nt
	v_cvt_pk_bf16_f32 v6, v6, v7
	v_cvt_pk_bf16_f32 v7, v8, v9
	v_add_co_u32_e32 v14, vcc, s4, v144
	v_cvt_pk_bf16_f32 v8, v2, v3
	s_nop 0
	v_addc_co_u32_e32 v15, vcc, 0, v145, vcc
	v_add_co_u32_e32 v2, vcc, 0x1e000, v144
	v_cvt_pk_bf16_f32 v126, v126, v127
	s_nop 0
	v_addc_co_u32_e32 v3, vcc, 0, v145, vcc
	v_cvt_pk_bf16_f32 v127, v128, v129
	v_cvt_pk_bf16_f32 v128, v122, v123
	v_cvt_pk_bf16_f32 v129, v124, v125
	v_cvt_pk_bf16_f32 v106, v118, v119
	v_cvt_pk_bf16_f32 v107, v120, v121
	v_cvt_pk_bf16_f32 v108, v114, v115
	v_cvt_pk_bf16_f32 v109, v116, v117
	v_cvt_pk_bf16_f32 v90, v102, v103
	v_cvt_pk_bf16_f32 v91, v104, v105
	v_cvt_pk_bf16_f32 v92, v98, v99
	v_cvt_pk_bf16_f32 v93, v100, v101
	v_cvt_pk_bf16_f32 v74, v86, v87
	v_cvt_pk_bf16_f32 v75, v88, v89
	v_cvt_pk_bf16_f32 v76, v82, v83
	v_cvt_pk_bf16_f32 v77, v84, v85
	v_cvt_pk_bf16_f32 v73, v68, v69
	v_cvt_pk_bf16_f32 v65, v60, v61
	v_cvt_pk_bf16_f32 v42, v54, v55
	v_cvt_pk_bf16_f32 v43, v56, v57
	v_cvt_pk_bf16_f32 v44, v50, v51
	v_cvt_pk_bf16_f32 v45, v52, v53
	v_cvt_pk_bf16_f32 v26, v38, v39
	v_cvt_pk_bf16_f32 v27, v40, v41
	v_cvt_pk_bf16_f32 v28, v34, v35
	v_cvt_pk_bf16_f32 v29, v36, v37
	v_cvt_pk_bf16_f32 v10, v22, v23
	v_cvt_pk_bf16_f32 v11, v24, v25
	v_cvt_pk_bf16_f32 v12, v18, v19
	v_cvt_pk_bf16_f32 v13, v20, v21
	v_cvt_pk_bf16_f32 v9, v4, v5
	s_and_b64 vcc, exec, s[34:35]
	s_mov_b32 s63, s38
	s_mov_b32 s40, s42
	s_mov_b64 s[4:5], s[48:49]
	s_mov_b64 s[44:45], s[46:47]
	global_store_dwordx4 v[144:145], v[126:129], off nt
	global_store_dwordx4 v[110:111], v[106:109], off nt
	global_store_dwordx4 v[94:95], v[90:93], off nt
	global_store_dwordx4 v[78:79], v[74:77], off nt
	global_store_dwordx4 v[66:67], v[70:73], off nt
	global_store_dwordx4 v[58:59], v[62:65], off nt
	global_store_dwordx4 v[46:47], v[42:45], off nt
	global_store_dwordx4 v[30:31], v[26:29], off nt
	global_store_dwordx4 v[14:15], v[10:13], off nt
	global_store_dwordx4 v[2:3], v[6:9], off nt
	s_cbranch_vccz .LBB0_59
	s_waitcnt vmcnt(0)
	s_cmpk_gt_u32 s25, 0xff
	s_cbranch_scc1 .LBB0_66
	s_barrier

; DI unsigned pk2(float a, float b) { f32x2 v = {a, b}; bf16v2 r = __builtin_convertvector(v, bf16v2); return __builtin_bit_cast(unsigned, r); }
;     DI void operator()(const f32x4 (&acc)[2][2][4][2], const Unit& u, int wr, int wc, int fr, int fq) const {
;     ...
;         const int row0 = u.pm * BM + wr * 64 + fr; const int col0 = u.pn * BM + wc * 32 + 8 * fq;
; #pragma unroll
;         for (int ai = 0; ai < 2; ++ai)
; #pragma unroll
;             for (int m = 0; m < 4; ++m) { bf16_t* rowp = O + (size_t)(row0 + ai * HALF + m * 16) * ldc + col0;
; #pragma unroll
;                 for (int bj = 0; bj < 2; ++bj) { const f32x4 v0 = acc[ai][bj][m][0], v1 = acc[ai][bj][m][1];
;                     u32x4 w; w.x = pk2(v0[0], v0[1]); w.y = pk2(v0[2], v0[3]); w.z = pk2(v1[0], v1[1]); w.w = pk2(v1[2], v1[3]);
;                     *(u32x4*)(rowp + bj * HALF) = w; } }
.LBB0_276:
	v_lshl_add_u32 v142, s53, 8, v138
	v_lshl_or_b32 v144, s54, 8, v140
	v_ashrrev_i32_e32 v143, 31, v142
	v_ashrrev_i32_e32 v145, 31, v144
	v_lshlrev_b64 v[146:147], 12, v[142:143]
	v_lshl_add_u64 v[146:147], s[70:71], 0, v[146:147]
	v_lshlrev_b64 v[144:145], 1, v[144:145]
	v_lshl_add_u64 v[146:147], v[146:147], 0, v[144:145]
	s_mov_b64 s[0:1], 0x80000
	v_cvt_pk_bf16_f32 v70, v70, v71
	v_cvt_pk_bf16_f32 v71, v72, v73
	v_cvt_pk_bf16_f32 v72, v66, v67
	v_lshl_add_u64 v[66:67], v[146:147], 0, s[0:1]
	s_mov_b32 s0, 0x80000
	v_cvt_pk_bf16_f32 v62, v62, v63
	v_cvt_pk_bf16_f32 v63, v64, v65
	v_cvt_pk_bf16_f32 v64, v58, v59
	v_add_co_u32_e32 v58, vcc, s0, v146
	v_cvt_pk_bf16_f32 v46, v46, v47
	v_cvt_pk_bf16_f32 v47, v48, v49
	v_cvt_pk_bf16_f32 v48, v42, v43
	v_cvt_pk_bf16_f32 v49, v44, v45
	s_mov_b64 s[0:1], 0x90000
	v_addc_co_u32_e32 v59, vcc, 0, v147, vcc
	global_store_dwordx4 v[66:67], v[46:49], off offset:256 nt
	v_cvt_pk_bf16_f32 v110, v110, v111
	v_cvt_pk_bf16_f32 v111, v112, v113
	v_lshl_add_u64 v[46:47], v[146:147], 0, s[0:1]
	s_mov_b32 s0, 0x90000
	v_cvt_pk_bf16_f32 v112, v106, v107
	v_or_b32_e32 v106, 16, v142
	v_add_co_u32_e32 v48, vcc, s0, v146
	v_cvt_pk_bf16_f32 v30, v30, v31
	v_cvt_pk_bf16_f32 v31, v32, v33
	v_cvt_pk_bf16_f32 v32, v26, v27
	v_cvt_pk_bf16_f32 v33, v28, v29
	s_mov_b64 s[0:1], 0xa0000
	v_ashrrev_i32_e32 v107, 31, v106
	v_cvt_pk_bf16_f32 v94, v94, v95
	v_cvt_pk_bf16_f32 v95, v96, v97
	v_cvt_pk_bf16_f32 v96, v90, v91
	v_or_b32_e32 v90, 32, v142
	v_addc_co_u32_e32 v49, vcc, 0, v147, vcc
	global_store_dwordx4 v[46:47], v[30:33], off offset:256 nt
	v_lshlrev_b64 v[106:107], 12, v[106:107]
	v_ashrrev_i32_e32 v91, 31, v90
	v_lshl_add_u64 v[30:31], v[146:147], 0, s[0:1]
	s_mov_b32 s0, 0xa0000
	v_cvt_pk_bf16_f32 v78, v78, v79
	v_cvt_pk_bf16_f32 v79, v80, v81
	v_cvt_pk_bf16_f32 v80, v74, v75
	v_or_b32_e32 v74, 48, v142
	v_add_co_u32_e32 v32, vcc, s0, v146
	v_cvt_pk_bf16_f32 v14, v14, v15
	v_cvt_pk_bf16_f32 v15, v16, v17
	v_cvt_pk_bf16_f32 v16, v10, v11
	v_cvt_pk_bf16_f32 v17, v12, v13
	s_mov_b64 s[0:1], 0xb0000
	v_cvt_pk_bf16_f32 v113, v108, v109
	v_lshl_add_u64 v[106:107], s[70:71], 0, v[106:107]
	v_lshlrev_b64 v[90:91], 12, v[90:91]
	v_ashrrev_i32_e32 v75, 31, v74
	v_addc_co_u32_e32 v33, vcc, 0, v147, vcc
	global_store_dwordx4 v[30:31], v[14:17], off offset:256 nt
	global_store_dwordx4 v[146:147], v[110:113], off offset:256 nt
	v_cvt_pk_bf16_f32 v97, v92, v93
	v_lshl_add_u64 v[14:15], v[146:147], 0, s[0:1]
	s_mov_b32 s0, 0xb0000
	v_lshl_add_u64 v[110:111], v[106:107], 0, v[144:145]
	v_lshl_add_u64 v[90:91], s[70:71], 0, v[90:91]
	v_lshlrev_b64 v[74:75], 12, v[74:75]
	v_add_co_u32_e32 v16, vcc, s0, v146
	global_store_dwordx4 v[110:111], v[94:97], off offset:256 nt
	v_cvt_pk_bf16_f32 v81, v76, v77
	v_lshl_add_u64 v[74:75], s[70:71], 0, v[74:75]
	v_lshl_add_u64 v[94:95], v[90:91], 0, v[144:145]
	v_addc_co_u32_e32 v17, vcc, 0, v147, vcc
	v_cvt_pk_bf16_f32 v126, v126, v127
	v_cvt_pk_bf16_f32 v127, v128, v129
	v_cvt_pk_bf16_f32 v128, v122, v123
	v_cvt_pk_bf16_f32 v129, v124, v125
	v_cvt_pk_bf16_f32 v106, v118, v119
	v_cvt_pk_bf16_f32 v107, v120, v121
	v_cvt_pk_bf16_f32 v108, v114, v115
	v_cvt_pk_bf16_f32 v109, v116, v117
	v_cvt_pk_bf16_f32 v90, v102, v103
	v_cvt_pk_bf16_f32 v91, v104, v105
	v_cvt_pk_bf16_f32 v92, v98, v99
	v_cvt_pk_bf16_f32 v93, v100, v101
	global_store_dwordx4 v[94:95], v[78:81], off offset:256 nt
	v_cvt_pk_bf16_f32 v76, v82, v83
	v_cvt_pk_bf16_f32 v77, v84, v85
	v_lshl_add_u64 v[78:79], v[74:75], 0, v[144:145]
	v_cvt_pk_bf16_f32 v74, v86, v87
	v_cvt_pk_bf16_f32 v75, v88, v89
	v_cvt_pk_bf16_f32 v73, v68, v69
	v_cvt_pk_bf16_f32 v65, v60, v61
	v_cvt_pk_bf16_f32 v42, v54, v55
	v_cvt_pk_bf16_f32 v43, v56, v57
	v_cvt_pk_bf16_f32 v44, v50, v51
	v_cvt_pk_bf16_f32 v45, v52, v53
	v_cvt_pk_bf16_f32 v26, v38, v39
	v_cvt_pk_bf16_f32 v27, v40, v41
	v_cvt_pk_bf16_f32 v28, v34, v35
	v_cvt_pk_bf16_f32 v29, v36, v37
	v_cvt_pk_bf16_f32 v10, v22, v23
	v_cvt_pk_bf16_f32 v11, v24, v25
	v_cvt_pk_bf16_f32 v12, v18, v19
	v_cvt_pk_bf16_f32 v13, v20, v21
	v_cvt_pk_bf16_f32 v6, v6, v7
	v_cvt_pk_bf16_f32 v7, v8, v9
	v_cvt_pk_bf16_f32 v8, v2, v3
	v_cvt_pk_bf16_f32 v9, v4, v5
	s_and_b64 vcc, exec, s[36:37]
	s_mov_b32 s54, s40
	s_mov_b32 s53, s55
	s_mov_b64 s[4:5], s[44:45]
	s_mov_b64 s[0:1], s[42:43]
	global_store_dwordx4 v[146:147], v[126:129], off nt
	global_store_dwordx4 v[110:111], v[106:109], off nt
	global_store_dwordx4 v[94:95], v[90:93], off nt
	global_store_dwordx4 v[78:79], v[74:77], off nt
	global_store_dwordx4 v[78:79], v[70:73], off offset:256 nt
	global_store_dwordx4 v[58:59], v[62:65], off nt
	global_store_dwordx4 v[48:49], v[42:45], off nt
	global_store_dwordx4 v[32:33], v[26:29], off nt
	global_store_dwordx4 v[16:17], v[10:13], off nt
	global_store_dwordx4 v[14:15], v[6:9], off offset:256 nt
	s_cbranch_vccnz .LBB0_289
